# v30
# speedup vs baseline: 1.0029x; 1.0025x over previous
; DEVI void attn_unit(const Params& p, char* lds, int au) {
;     ...
; #pragma unroll
;     for (int qb = 0; qb < 2; ++qb) {
;       u32x4 t0, t1;
; #pragma unroll
;       for (int kb = 0; kb < 4; ++kb) {
;         f32x4 e;
;         e[0] = __builtin_amdgcn_exp2f(sc[kb][qb][0]);
;         e[1] = __builtin_amdgcn_exp2f(sc[kb][qb][1]);
;         e[2] = __builtin_amdgcn_exp2f(sc[kb][qb][2]);
;         e[3] = __builtin_amdgcn_exp2f(sc[kb][qb][3]);
;         lsum[qb] += e;
;         uint32_t w0 = pk2(e[0], e[1]), w1 = pk2(e[2], e[3]);
;         if (kb == 0) { t0[0] = w0; t0[1] = w1; }
;         if (kb == 1) { t0[2] = w0; t0[3] = w1; }
;         if (kb == 2) { t1[0] = w0; t1[1] = w1; }
;         if (kb == 3) { t1[2] = w0; t1[3] = w1; }
;       }
;       pf[qb][0] = __builtin_bit_cast(bf16x8, t0);
;       pf[qb][1] = __builtin_bit_cast(bf16x8, t1);
;     }
;     if (!typeB) PVSTEP(lds + 32768 + vcur * 16384);
.LBB0_217:
	v_exp_f32_e32 v146, v90
	v_exp_f32_e32 v147, v91
	v_exp_f32_e32 v148, v92
	v_exp_f32_e32 v149, v93
	v_exp_f32_e32 v118, v118
	v_exp_f32_e32 v119, v119
	v_exp_f32_e32 v120, v120
	v_exp_f32_e32 v121, v121
	v_exp_f32_e32 v150, v98
	v_exp_f32_e32 v151, v99
	v_exp_f32_e32 v152, v100
	v_exp_f32_e32 v153, v101
	v_exp_f32_e32 v114, v114
	v_exp_f32_e32 v115, v115
	v_exp_f32_e32 v116, v116
	v_exp_f32_e32 v117, v117
	v_exp_f32_e32 v154, v110
	v_exp_f32_e32 v155, v111
	v_exp_f32_e32 v156, v112
	v_exp_f32_e32 v157, v113
	v_exp_f32_e32 v106, v106
	v_exp_f32_e32 v107, v107
	v_exp_f32_e32 v108, v108
	v_exp_f32_e32 v109, v109
	v_exp_f32_e32 v158, v102
	v_exp_f32_e32 v159, v103
	v_exp_f32_e32 v160, v104
	v_exp_f32_e32 v161, v105
	v_exp_f32_e32 v94, v94
	v_exp_f32_e32 v95, v95
	v_exp_f32_e32 v96, v96
	v_exp_f32_e32 v97, v97
	v_cvt_pk_bf16_f32 v90, v146, v147
	v_cvt_pk_bf16_f32 v91, v148, v149
	v_cvt_pk_bf16_f32 v92, v118, v119
	v_cvt_pk_bf16_f32 v93, v120, v121
	v_cvt_pk_bf16_f32 v98, v150, v151
	v_cvt_pk_bf16_f32 v99, v152, v153
	v_cvt_pk_bf16_f32 v100, v114, v115
	v_cvt_pk_bf16_f32 v101, v116, v117
	v_cvt_pk_bf16_f32 v110, v154, v155
	v_cvt_pk_bf16_f32 v111, v156, v157
	v_cvt_pk_bf16_f32 v112, v106, v107
	v_cvt_pk_bf16_f32 v113, v108, v109
	v_cvt_pk_bf16_f32 v102, v158, v159
	v_cvt_pk_bf16_f32 v103, v160, v161
	v_cvt_pk_bf16_f32 v104, v94, v95
	v_cvt_pk_bf16_f32 v105, v96, v97
	v_pk_add_f32 v[138:139], v[148:149], v[138:139]
	v_pk_add_f32 v[136:137], v[146:147], v[136:137]
	v_pk_add_f32 v[120:121], v[120:121], v[138:139]
	v_pk_add_f32 v[118:119], v[118:119], v[136:137]
	v_pk_add_f32 v[120:121], v[152:153], v[120:121]
	v_pk_add_f32 v[118:119], v[150:151], v[118:119]
	v_pk_add_f32 v[138:139], v[116:117], v[120:121]
	v_pk_add_f32 v[136:137], v[114:115], v[118:119]
	v_pk_add_f32 v[114:115], v[156:157], v[142:143]
	v_pk_add_f32 v[116:117], v[154:155], v[140:141]
	v_pk_add_f32 v[108:109], v[108:109], v[114:115]
	v_pk_add_f32 v[106:107], v[106:107], v[116:117]
	v_pk_add_f32 v[108:109], v[160:161], v[108:109]
	v_pk_add_f32 v[106:107], v[158:159], v[106:107]
	v_pk_add_f32 v[140:141], v[94:95], v[106:107]
	v_pk_add_f32 v[142:143], v[96:97], v[108:109]
	s_and_b64 vcc, exec, s[12:13]
	s_cbranch_vccnz .LBB0_219
	s_waitcnt lgkmcnt(4)
	s_setprio 1
	v_mfma_f32_16x16x32_bf16 v[82:85], v[168:171], v[90:93], v[82:85]
	v_mfma_f32_16x16x32_bf16 v[78:81], v[168:171], v[110:113], v[78:81]
	v_mfma_f32_16x16x32_bf16 v[74:77], v[186:189], v[90:93], v[74:77]
	v_mfma_f32_16x16x32_bf16 v[70:73], v[186:189], v[110:113], v[70:73]
	v_mfma_f32_16x16x32_bf16 v[66:69], v[198:201], v[90:93], v[66:69]
	v_mfma_f32_16x16x32_bf16 v[58:61], v[198:201], v[110:113], v[58:61]
	v_mfma_f32_16x16x32_bf16 v[54:57], v[202:205], v[90:93], v[54:57]
	v_mfma_f32_16x16x32_bf16 v[50:53], v[202:205], v[110:113], v[50:53]
	ds_read_b128 v[168:171], v163 offset:40960
	ds_read_b128 v[186:189], v163 offset:43008
	ds_read_b128 v[198:201], v163 offset:45056
	ds_read_b128 v[202:205], v163 offset:47104
	s_waitcnt lgkmcnt(4)
	v_mfma_f32_16x16x32_bf16 v[82:85], v[190:193], v[98:101], v[82:85]
	v_mfma_f32_16x16x32_bf16 v[78:81], v[190:193], v[102:105], v[78:81]
	v_mfma_f32_16x16x32_bf16 v[74:77], v[194:197], v[98:101], v[74:77]
	v_mfma_f32_16x16x32_bf16 v[70:73], v[194:197], v[102:105], v[70:73]
	v_mfma_f32_16x16x32_bf16 v[66:69], v[206:209], v[98:101], v[66:69]
	v_mfma_f32_16x16x32_bf16 v[58:61], v[206:209], v[102:105], v[58:61]
	v_mfma_f32_16x16x32_bf16 v[54:57], v[210:213], v[98:101], v[54:57]
	v_mfma_f32_16x16x32_bf16 v[50:53], v[210:213], v[102:105], v[50:53]
	ds_read_b128 v[190:193], v162 offset:40960
	ds_read_b128 v[194:197], v162 offset:43008
	ds_read_b128 v[206:209], v162 offset:45056
	ds_read_b128 v[210:213], v162 offset:47104
	s_waitcnt lgkmcnt(4)
	v_mfma_f32_16x16x32_bf16 v[46:49], v[168:171], v[90:93], v[46:49]
	v_mfma_f32_16x16x32_bf16 v[42:45], v[168:171], v[110:113], v[42:45]
	v_mfma_f32_16x16x32_bf16 v[38:41], v[186:189], v[90:93], v[38:41]
	v_mfma_f32_16x16x32_bf16 v[34:37], v[186:189], v[110:113], v[34:37]
	v_mfma_f32_16x16x32_bf16 v[30:33], v[198:201], v[90:93], v[30:33]
	v_mfma_f32_16x16x32_bf16 v[26:29], v[198:201], v[110:113], v[26:29]
	v_mfma_f32_16x16x32_bf16 v[22:25], v[202:205], v[90:93], v[22:25]
	v_mfma_f32_16x16x32_bf16 v[2:5], v[202:205], v[110:113], v[2:5]
	s_waitcnt lgkmcnt(0)
	v_mfma_f32_16x16x32_bf16 v[46:49], v[190:193], v[98:101], v[46:49]
	v_mfma_f32_16x16x32_bf16 v[42:45], v[190:193], v[102:105], v[42:45]
	v_mfma_f32_16x16x32_bf16 v[38:41], v[194:197], v[98:101], v[38:41]
	v_mfma_f32_16x16x32_bf16 v[34:37], v[194:197], v[102:105], v[34:37]
	v_mfma_f32_16x16x32_bf16 v[30:33], v[206:209], v[98:101], v[30:33]
	v_mfma_f32_16x16x32_bf16 v[26:29], v[206:209], v[102:105], v[26:29]
	v_mfma_f32_16x16x32_bf16 v[22:25], v[210:213], v[98:101], v[22:25]
	v_mfma_f32_16x16x32_bf16 v[2:5], v[210:213], v[102:105], v[2:5]
	s_setprio 0
.LBB0_219:
.Lpv_done:
	s_add_i32 s8, s8, -1
	s_add_i32 s2, s10, s14
	s_cmp_eq_u32 s2, 2
	s_waitcnt vmcnt(0)
	s_barrier
	s_cbranch_scc1 .LBB0_223
	s_mov_b32 s15, s11
	s_mov_b32 s18, s14
	s_branch .LBB0_206
